# sgu spatial phase: all 8 V-row loads of a unit issued up front (unrolled, counted vmcnt) instead of 8 serial round trips; plus prologue gain prefetch and ffn-up store permutation
# speedup vs baseline: 1.0204x; 1.0046x over previous
.LBB0_486:
	s_waitcnt lgkmcnt(0)
	s_barrier
	global_load_dwordx4 v[0:3], v[108:109], off
	global_load_dwordx4 v[4:7], v[108:109], off offset:16
	global_load_dwordx4 v[8:11], v[110:111], off
	global_load_dwordx4 v[12:15], v[110:111], off offset:16
	s_lshl_b64 s[4:5], s[8:9], 19
	v_lshl_add_u64 v[20:21], v[130:131], 0, s[4:5]
	s_mov_b32 s4, 0
	v_mov_b32_e32 v22, v86
	s_mov_b64 s[100:101], 0x20000
	v_add_co_u32_e32 v24, vcc, 0xffff0000, v20
	s_nop 1
	v_addc_co_u32_e32 v25, vcc, -1, v21, vcc
	v_mov_b32_e32 v26, v20
	v_mov_b32_e32 v27, v21
	global_load_dwordx4 v[216:219], v[24:25], off
	global_load_dwordx4 v[220:223], v[26:27], off
	v_lshl_add_u64 v[24:25], v[24:25], 0, s[100:101]
	v_lshl_add_u64 v[26:27], v[26:27], 0, s[100:101]
	global_load_dwordx4 v[224:227], v[24:25], off
	global_load_dwordx4 v[228:231], v[26:27], off
	v_lshl_add_u64 v[24:25], v[24:25], 0, s[100:101]
	v_lshl_add_u64 v[26:27], v[26:27], 0, s[100:101]
	global_load_dwordx4 v[232:235], v[24:25], off
	global_load_dwordx4 v[236:239], v[26:27], off
	v_lshl_add_u64 v[24:25], v[24:25], 0, s[100:101]
	v_lshl_add_u64 v[26:27], v[26:27], 0, s[100:101]
	global_load_dwordx4 v[240:243], v[24:25], off
	global_load_dwordx4 v[244:247], v[26:27], off
.LBB0_487:
	v_add_co_u32_e32 v16, vcc, 0xffff0000, v20
	v_add_u32_e32 v23, s4, v170
	s_nop 0
	v_addc_co_u32_e32 v17, vcc, -1, v21, vcc
	v_add_u32_e32 v24, 0x19000, v23
	ds_read_b32 v24, v24
	v_add_u32_e32 v25, 0x19200, v23
	ds_read_b32 v25, v25
	v_lshrrev_b32_e32 v26, 3, v22
	v_xor_b32_e32 v26, v26, v168
	v_lshlrev_b32_e32 v26, 4, v26
	v_add_u32_e32 v28, v169, v26
	s_addk_i32 s4, 0x80
	s_mov_b64 s[8:9], 0x20000
	s_waitcnt vmcnt(7)
	v_mov_b32_e32 v16, v216
	v_mov_b32_e32 v17, v217
	v_mov_b32_e32 v18, v218
	v_mov_b32_e32 v19, v219
	v_lshlrev_b32_e32 v27, 16, v16
	s_waitcnt lgkmcnt(1)
	v_sub_f32_e32 v27, v27, v24
	v_and_b32_e32 v16, 0xffff0000, v16
	s_waitcnt lgkmcnt(0)
	v_mul_f32_e32 v27, v25, v27
	v_sub_f32_e32 v16, v16, v24
	v_fma_f32 v27, v0, v27, v8
	v_mul_f32_e32 v16, v25, v16
	v_cvt_pk_bf16_f32 v27, v27, v27
	v_fma_f32 v16, v1, v16, v9
	ds_write_b16 v28, v27 offset:34816
	v_cvt_pk_bf16_f32 v16, v16, v16
	v_xad_u32 v27, v26, 16, v169
	ds_write_b16 v27, v16 offset:35072
	v_lshlrev_b32_e32 v16, 16, v17
	v_sub_f32_e32 v16, v16, v24
	v_mul_f32_e32 v16, v25, v16
	v_fma_f32 v16, v2, v16, v10
	v_cvt_pk_bf16_f32 v16, v16, v16
	v_xad_u32 v27, v26, 32, v169
	ds_write_b16 v27, v16 offset:35328
	v_and_b32_e32 v16, 0xffff0000, v17
	v_sub_f32_e32 v16, v16, v24
	v_mul_f32_e32 v16, v25, v16
	v_fma_f32 v16, v3, v16, v11
	v_cvt_pk_bf16_f32 v16, v16, v16
	v_xad_u32 v17, v26, 48, v169
	ds_write_b16 v17, v16 offset:35584
	v_lshlrev_b32_e32 v16, 16, v18
	v_sub_f32_e32 v16, v16, v24
	v_mul_f32_e32 v16, v25, v16
	v_fma_f32 v16, v4, v16, v12
	v_cvt_pk_bf16_f32 v16, v16, v16
	v_xad_u32 v17, v26, 64, v169
	ds_write_b16 v17, v16 offset:35840
	v_and_b32_e32 v16, 0xffff0000, v18
	v_sub_f32_e32 v16, v16, v24
	v_mul_f32_e32 v16, v25, v16
	v_fma_f32 v16, v5, v16, v13
	v_cvt_pk_bf16_f32 v16, v16, v16
	v_xad_u32 v17, v26, s20, v169
	ds_write_b16 v17, v16 offset:36096
	v_lshlrev_b32_e32 v16, 16, v19
	v_sub_f32_e32 v16, v16, v24
	v_mul_f32_e32 v16, v25, v16
	v_fma_f32 v16, v6, v16, v14
	v_cvt_pk_bf16_f32 v16, v16, v16
	v_xad_u32 v17, v26, s21, v169
	ds_write_b16 v17, v16 offset:36352
	v_and_b32_e32 v16, 0xffff0000, v19
	v_sub_f32_e32 v16, v16, v24
	v_mul_f32_e32 v16, v25, v16
	v_fma_f32 v16, v7, v16, v15
	v_cvt_pk_bf16_f32 v16, v16, v16
	v_xad_u32 v17, v26, s22, v169
	ds_write_b16 v17, v16 offset:36608
	v_add_u32_e32 v25, 0x19040, v23
	ds_read_b32 v25, v25
	v_add_u32_e32 v23, 0x19240, v23
	ds_read_b32 v23, v23
	v_add_u32_e32 v24, 16, v22
	v_lshrrev_b32_e32 v24, 3, v24
	v_xor_b32_e32 v24, v24, v168
	v_lshlrev_b32_e32 v24, 4, v24
	v_add_u32_e32 v27, v169, v24
	v_add_u32_e32 v22, 32, v22
	v_lshl_add_u64 v[20:21], v[20:21], 0, s[8:9]
	s_waitcnt vmcnt(6)
	v_mov_b32_e32 v16, v220
	v_mov_b32_e32 v17, v221
	v_mov_b32_e32 v18, v222
	v_mov_b32_e32 v19, v223
	v_lshlrev_b32_e32 v26, 16, v16
	s_waitcnt lgkmcnt(1)
	v_sub_f32_e32 v26, v26, v25
	v_and_b32_e32 v16, 0xffff0000, v16
	s_waitcnt lgkmcnt(0)
	v_mul_f32_e32 v26, v23, v26
	v_sub_f32_e32 v16, v16, v25
	v_fma_f32 v26, v0, v26, v8
	v_mul_f32_e32 v16, v23, v16
	v_cvt_pk_bf16_f32 v26, v26, v26
	v_fma_f32 v16, v1, v16, v9
	ds_write_b16 v27, v26 offset:34816
	v_cvt_pk_bf16_f32 v16, v16, v16
	v_xad_u32 v26, v24, 16, v169
	ds_write_b16 v26, v16 offset:35072
	v_lshlrev_b32_e32 v16, 16, v17
	v_sub_f32_e32 v16, v16, v25
	v_mul_f32_e32 v16, v23, v16
	v_fma_f32 v16, v2, v16, v10
	v_cvt_pk_bf16_f32 v16, v16, v16
	v_xad_u32 v26, v24, 32, v169
	ds_write_b16 v26, v16 offset:35328
	v_and_b32_e32 v16, 0xffff0000, v17
	v_sub_f32_e32 v16, v16, v25
	v_mul_f32_e32 v16, v23, v16
	v_fma_f32 v16, v3, v16, v11
	v_cvt_pk_bf16_f32 v16, v16, v16
	v_xad_u32 v17, v24, 48, v169
	ds_write_b16 v17, v16 offset:35584
	v_lshlrev_b32_e32 v16, 16, v18
	v_sub_f32_e32 v16, v16, v25
	v_mul_f32_e32 v16, v23, v16
	v_fma_f32 v16, v4, v16, v12
	v_cvt_pk_bf16_f32 v16, v16, v16
	v_xad_u32 v17, v24, 64, v169
	ds_write_b16 v17, v16 offset:35840
	v_and_b32_e32 v16, 0xffff0000, v18
	v_sub_f32_e32 v16, v16, v25
	v_mul_f32_e32 v16, v23, v16
	v_fma_f32 v16, v5, v16, v13
	v_cvt_pk_bf16_f32 v16, v16, v16
	v_xad_u32 v17, v24, s20, v169
	ds_write_b16 v17, v16 offset:36096
	v_lshlrev_b32_e32 v16, 16, v19
	v_sub_f32_e32 v16, v16, v25
	v_mul_f32_e32 v16, v23, v16
	v_fma_f32 v16, v6, v16, v14
	v_cvt_pk_bf16_f32 v16, v16, v16
	v_xad_u32 v17, v24, s21, v169
	ds_write_b16 v17, v16 offset:36352
	v_and_b32_e32 v16, 0xffff0000, v19
	v_sub_f32_e32 v16, v16, v25
	v_mul_f32_e32 v16, v23, v16
	v_fma_f32 v16, v7, v16, v15
	v_xad_u32 v17, v24, s22, v169
	v_cvt_pk_bf16_f32 v16, v16, v16
	ds_write_b16 v17, v16 offset:36608
	v_add_co_u32_e32 v16, vcc, 0xffff0000, v20
	v_add_u32_e32 v23, s4, v170
	s_nop 0
	v_addc_co_u32_e32 v17, vcc, -1, v21, vcc
	v_add_u32_e32 v24, 0x19000, v23
	ds_read_b32 v24, v24
	v_add_u32_e32 v25, 0x19200, v23
	ds_read_b32 v25, v25
	v_lshrrev_b32_e32 v26, 3, v22
	v_xor_b32_e32 v26, v26, v168
	v_lshlrev_b32_e32 v26, 4, v26
	v_add_u32_e32 v28, v169, v26
	s_addk_i32 s4, 0x80
	s_mov_b64 s[8:9], 0x20000
	s_waitcnt vmcnt(5)
	v_mov_b32_e32 v16, v224
	v_mov_b32_e32 v17, v225
	v_mov_b32_e32 v18, v226
	v_mov_b32_e32 v19, v227
	v_lshlrev_b32_e32 v27, 16, v16
	s_waitcnt lgkmcnt(1)
	v_sub_f32_e32 v27, v27, v24
	v_and_b32_e32 v16, 0xffff0000, v16
	s_waitcnt lgkmcnt(0)
	v_mul_f32_e32 v27, v25, v27
	v_sub_f32_e32 v16, v16, v24
	v_fma_f32 v27, v0, v27, v8
	v_mul_f32_e32 v16, v25, v16
	v_cvt_pk_bf16_f32 v27, v27, v27
	v_fma_f32 v16, v1, v16, v9
	ds_write_b16 v28, v27 offset:34816
	v_cvt_pk_bf16_f32 v16, v16, v16
	v_xad_u32 v27, v26, 16, v169
	ds_write_b16 v27, v16 offset:35072
	v_lshlrev_b32_e32 v16, 16, v17
	v_sub_f32_e32 v16, v16, v24
	v_mul_f32_e32 v16, v25, v16
	v_fma_f32 v16, v2, v16, v10
	v_cvt_pk_bf16_f32 v16, v16, v16
	v_xad_u32 v27, v26, 32, v169
	ds_write_b16 v27, v16 offset:35328
	v_and_b32_e32 v16, 0xffff0000, v17
	v_sub_f32_e32 v16, v16, v24
	v_mul_f32_e32 v16, v25, v16
	v_fma_f32 v16, v3, v16, v11
	v_cvt_pk_bf16_f32 v16, v16, v16
	v_xad_u32 v17, v26, 48, v169
	ds_write_b16 v17, v16 offset:35584
	v_lshlrev_b32_e32 v16, 16, v18
	v_sub_f32_e32 v16, v16, v24
	v_mul_f32_e32 v16, v25, v16
	v_fma_f32 v16, v4, v16, v12
	v_cvt_pk_bf16_f32 v16, v16, v16
	v_xad_u32 v17, v26, 64, v169
	ds_write_b16 v17, v16 offset:35840
	v_and_b32_e32 v16, 0xffff0000, v18
	v_sub_f32_e32 v16, v16, v24
	v_mul_f32_e32 v16, v25, v16
	v_fma_f32 v16, v5, v16, v13
	v_cvt_pk_bf16_f32 v16, v16, v16
	v_xad_u32 v17, v26, s20, v169
	ds_write_b16 v17, v16 offset:36096
	v_lshlrev_b32_e32 v16, 16, v19
	v_sub_f32_e32 v16, v16, v24
	v_mul_f32_e32 v16, v25, v16
	v_fma_f32 v16, v6, v16, v14
	v_cvt_pk_bf16_f32 v16, v16, v16
	v_xad_u32 v17, v26, s21, v169
	ds_write_b16 v17, v16 offset:36352
	v_and_b32_e32 v16, 0xffff0000, v19
	v_sub_f32_e32 v16, v16, v24
	v_mul_f32_e32 v16, v25, v16
	v_fma_f32 v16, v7, v16, v15
	v_cvt_pk_bf16_f32 v16, v16, v16
	v_xad_u32 v17, v26, s22, v169
	ds_write_b16 v17, v16 offset:36608
	v_add_u32_e32 v25, 0x19040, v23
	ds_read_b32 v25, v25
	v_add_u32_e32 v23, 0x19240, v23
	ds_read_b32 v23, v23
	v_add_u32_e32 v24, 16, v22
	v_lshrrev_b32_e32 v24, 3, v24
	v_xor_b32_e32 v24, v24, v168
	v_lshlrev_b32_e32 v24, 4, v24
	v_add_u32_e32 v27, v169, v24
	v_add_u32_e32 v22, 32, v22
	v_lshl_add_u64 v[20:21], v[20:21], 0, s[8:9]
	s_waitcnt vmcnt(4)
	v_mov_b32_e32 v16, v228
	v_mov_b32_e32 v17, v229
	v_mov_b32_e32 v18, v230
	v_mov_b32_e32 v19, v231
	v_lshlrev_b32_e32 v26, 16, v16
	s_waitcnt lgkmcnt(1)
	v_sub_f32_e32 v26, v26, v25
	v_and_b32_e32 v16, 0xffff0000, v16
	s_waitcnt lgkmcnt(0)
	v_mul_f32_e32 v26, v23, v26
	v_sub_f32_e32 v16, v16, v25
	v_fma_f32 v26, v0, v26, v8
	v_mul_f32_e32 v16, v23, v16
	v_cvt_pk_bf16_f32 v26, v26, v26
	v_fma_f32 v16, v1, v16, v9
	ds_write_b16 v27, v26 offset:34816
	v_cvt_pk_bf16_f32 v16, v16, v16
	v_xad_u32 v26, v24, 16, v169
	ds_write_b16 v26, v16 offset:35072
	v_lshlrev_b32_e32 v16, 16, v17
	v_sub_f32_e32 v16, v16, v25
	v_mul_f32_e32 v16, v23, v16
	v_fma_f32 v16, v2, v16, v10
	v_cvt_pk_bf16_f32 v16, v16, v16
	v_xad_u32 v26, v24, 32, v169
	ds_write_b16 v26, v16 offset:35328
	v_and_b32_e32 v16, 0xffff0000, v17
	v_sub_f32_e32 v16, v16, v25
	v_mul_f32_e32 v16, v23, v16
	v_fma_f32 v16, v3, v16, v11
	v_cvt_pk_bf16_f32 v16, v16, v16
	v_xad_u32 v17, v24, 48, v169
	ds_write_b16 v17, v16 offset:35584
	v_lshlrev_b32_e32 v16, 16, v18
	v_sub_f32_e32 v16, v16, v25
	v_mul_f32_e32 v16, v23, v16
	v_fma_f32 v16, v4, v16, v12
	v_cvt_pk_bf16_f32 v16, v16, v16
	v_xad_u32 v17, v24, 64, v169
	ds_write_b16 v17, v16 offset:35840
	v_and_b32_e32 v16, 0xffff0000, v18
	v_sub_f32_e32 v16, v16, v25
	v_mul_f32_e32 v16, v23, v16
	v_fma_f32 v16, v5, v16, v13
	v_cvt_pk_bf16_f32 v16, v16, v16
	v_xad_u32 v17, v24, s20, v169
	ds_write_b16 v17, v16 offset:36096
	v_lshlrev_b32_e32 v16, 16, v19
	v_sub_f32_e32 v16, v16, v25
	v_mul_f32_e32 v16, v23, v16
	v_fma_f32 v16, v6, v16, v14
	v_cvt_pk_bf16_f32 v16, v16, v16
	v_xad_u32 v17, v24, s21, v169
	ds_write_b16 v17, v16 offset:36352
	v_and_b32_e32 v16, 0xffff0000, v19
	v_sub_f32_e32 v16, v16, v25
	v_mul_f32_e32 v16, v23, v16
	v_fma_f32 v16, v7, v16, v15
	v_xad_u32 v17, v24, s22, v169
	v_cvt_pk_bf16_f32 v16, v16, v16
	ds_write_b16 v17, v16 offset:36608
	v_add_co_u32_e32 v16, vcc, 0xffff0000, v20
	v_add_u32_e32 v23, s4, v170
	s_nop 0
	v_addc_co_u32_e32 v17, vcc, -1, v21, vcc
	v_add_u32_e32 v24, 0x19000, v23
	ds_read_b32 v24, v24
	v_add_u32_e32 v25, 0x19200, v23
	ds_read_b32 v25, v25
	v_lshrrev_b32_e32 v26, 3, v22
	v_xor_b32_e32 v26, v26, v168
	v_lshlrev_b32_e32 v26, 4, v26
	v_add_u32_e32 v28, v169, v26
	s_addk_i32 s4, 0x80
	s_mov_b64 s[8:9], 0x20000
	s_waitcnt vmcnt(3)
	v_mov_b32_e32 v16, v232
	v_mov_b32_e32 v17, v233
	v_mov_b32_e32 v18, v234
	v_mov_b32_e32 v19, v235
	v_lshlrev_b32_e32 v27, 16, v16
	s_waitcnt lgkmcnt(1)
	v_sub_f32_e32 v27, v27, v24
	v_and_b32_e32 v16, 0xffff0000, v16
	s_waitcnt lgkmcnt(0)
	v_mul_f32_e32 v27, v25, v27
	v_sub_f32_e32 v16, v16, v24
	v_fma_f32 v27, v0, v27, v8
	v_mul_f32_e32 v16, v25, v16
	v_cvt_pk_bf16_f32 v27, v27, v27
	v_fma_f32 v16, v1, v16, v9
	ds_write_b16 v28, v27 offset:34816
	v_cvt_pk_bf16_f32 v16, v16, v16
	v_xad_u32 v27, v26, 16, v169
	ds_write_b16 v27, v16 offset:35072
	v_lshlrev_b32_e32 v16, 16, v17
	v_sub_f32_e32 v16, v16, v24
	v_mul_f32_e32 v16, v25, v16
	v_fma_f32 v16, v2, v16, v10
	v_cvt_pk_bf16_f32 v16, v16, v16
	v_xad_u32 v27, v26, 32, v169
	ds_write_b16 v27, v16 offset:35328
	v_and_b32_e32 v16, 0xffff0000, v17
	v_sub_f32_e32 v16, v16, v24
	v_mul_f32_e32 v16, v25, v16
	v_fma_f32 v16, v3, v16, v11
	v_cvt_pk_bf16_f32 v16, v16, v16
	v_xad_u32 v17, v26, 48, v169
	ds_write_b16 v17, v16 offset:35584
	v_lshlrev_b32_e32 v16, 16, v18
	v_sub_f32_e32 v16, v16, v24
	v_mul_f32_e32 v16, v25, v16
	v_fma_f32 v16, v4, v16, v12
	v_cvt_pk_bf16_f32 v16, v16, v16
	v_xad_u32 v17, v26, 64, v169
	ds_write_b16 v17, v16 offset:35840
	v_and_b32_e32 v16, 0xffff0000, v18
	v_sub_f32_e32 v16, v16, v24
	v_mul_f32_e32 v16, v25, v16
	v_fma_f32 v16, v5, v16, v13
	v_cvt_pk_bf16_f32 v16, v16, v16
	v_xad_u32 v17, v26, s20, v169
	ds_write_b16 v17, v16 offset:36096
	v_lshlrev_b32_e32 v16, 16, v19
	v_sub_f32_e32 v16, v16, v24
	v_mul_f32_e32 v16, v25, v16
	v_fma_f32 v16, v6, v16, v14
	v_cvt_pk_bf16_f32 v16, v16, v16
	v_xad_u32 v17, v26, s21, v169
	ds_write_b16 v17, v16 offset:36352
	v_and_b32_e32 v16, 0xffff0000, v19
	v_sub_f32_e32 v16, v16, v24
	v_mul_f32_e32 v16, v25, v16
	v_fma_f32 v16, v7, v16, v15
	v_cvt_pk_bf16_f32 v16, v16, v16
	v_xad_u32 v17, v26, s22, v169
	ds_write_b16 v17, v16 offset:36608
	v_add_u32_e32 v25, 0x19040, v23
	ds_read_b32 v25, v25
	v_add_u32_e32 v23, 0x19240, v23
	ds_read_b32 v23, v23
	v_add_u32_e32 v24, 16, v22
	v_lshrrev_b32_e32 v24, 3, v24
	v_xor_b32_e32 v24, v24, v168
	v_lshlrev_b32_e32 v24, 4, v24
	v_add_u32_e32 v27, v169, v24
	v_add_u32_e32 v22, 32, v22
	v_lshl_add_u64 v[20:21], v[20:21], 0, s[8:9]
	s_waitcnt vmcnt(2)
	v_mov_b32_e32 v16, v236
	v_mov_b32_e32 v17, v237
	v_mov_b32_e32 v18, v238
	v_mov_b32_e32 v19, v239
	v_lshlrev_b32_e32 v26, 16, v16
	s_waitcnt lgkmcnt(1)
	v_sub_f32_e32 v26, v26, v25
	v_and_b32_e32 v16, 0xffff0000, v16
	s_waitcnt lgkmcnt(0)
	v_mul_f32_e32 v26, v23, v26
	v_sub_f32_e32 v16, v16, v25
	v_fma_f32 v26, v0, v26, v8
	v_mul_f32_e32 v16, v23, v16
	v_cvt_pk_bf16_f32 v26, v26, v26
	v_fma_f32 v16, v1, v16, v9
	ds_write_b16 v27, v26 offset:34816
	v_cvt_pk_bf16_f32 v16, v16, v16
	v_xad_u32 v26, v24, 16, v169
	ds_write_b16 v26, v16 offset:35072
	v_lshlrev_b32_e32 v16, 16, v17
	v_sub_f32_e32 v16, v16, v25
	v_mul_f32_e32 v16, v23, v16
	v_fma_f32 v16, v2, v16, v10
	v_cvt_pk_bf16_f32 v16, v16, v16
	v_xad_u32 v26, v24, 32, v169
	ds_write_b16 v26, v16 offset:35328
	v_and_b32_e32 v16, 0xffff0000, v17
	v_sub_f32_e32 v16, v16, v25
	v_mul_f32_e32 v16, v23, v16
	v_fma_f32 v16, v3, v16, v11
	v_cvt_pk_bf16_f32 v16, v16, v16
	v_xad_u32 v17, v24, 48, v169
	ds_write_b16 v17, v16 offset:35584
	v_lshlrev_b32_e32 v16, 16, v18
	v_sub_f32_e32 v16, v16, v25
	v_mul_f32_e32 v16, v23, v16
	v_fma_f32 v16, v4, v16, v12
	v_cvt_pk_bf16_f32 v16, v16, v16
	v_xad_u32 v17, v24, 64, v169
	ds_write_b16 v17, v16 offset:35840
	v_and_b32_e32 v16, 0xffff0000, v18
	v_sub_f32_e32 v16, v16, v25
	v_mul_f32_e32 v16, v23, v16
	v_fma_f32 v16, v5, v16, v13
	v_cvt_pk_bf16_f32 v16, v16, v16
	v_xad_u32 v17, v24, s20, v169
	ds_write_b16 v17, v16 offset:36096
	v_lshlrev_b32_e32 v16, 16, v19
	v_sub_f32_e32 v16, v16, v25
	v_mul_f32_e32 v16, v23, v16
	v_fma_f32 v16, v6, v16, v14
	v_cvt_pk_bf16_f32 v16, v16, v16
	v_xad_u32 v17, v24, s21, v169
	ds_write_b16 v17, v16 offset:36352
	v_and_b32_e32 v16, 0xffff0000, v19
	v_sub_f32_e32 v16, v16, v25
	v_mul_f32_e32 v16, v23, v16
	v_fma_f32 v16, v7, v16, v15
	v_xad_u32 v17, v24, s22, v169
	v_cvt_pk_bf16_f32 v16, v16, v16
	ds_write_b16 v17, v16 offset:36608
	v_add_co_u32_e32 v16, vcc, 0xffff0000, v20
	v_add_u32_e32 v23, s4, v170
	s_nop 0
	v_addc_co_u32_e32 v17, vcc, -1, v21, vcc
	v_add_u32_e32 v24, 0x19000, v23
	ds_read_b32 v24, v24
	v_add_u32_e32 v25, 0x19200, v23
	ds_read_b32 v25, v25
	v_lshrrev_b32_e32 v26, 3, v22
	v_xor_b32_e32 v26, v26, v168
	v_lshlrev_b32_e32 v26, 4, v26
	v_add_u32_e32 v28, v169, v26
	s_addk_i32 s4, 0x80
	s_mov_b64 s[8:9], 0x20000
	s_waitcnt vmcnt(1)
	v_mov_b32_e32 v16, v240
	v_mov_b32_e32 v17, v241
	v_mov_b32_e32 v18, v242
	v_mov_b32_e32 v19, v243
	v_lshlrev_b32_e32 v27, 16, v16
	s_waitcnt lgkmcnt(1)
	v_sub_f32_e32 v27, v27, v24
	v_and_b32_e32 v16, 0xffff0000, v16
	s_waitcnt lgkmcnt(0)
	v_mul_f32_e32 v27, v25, v27
	v_sub_f32_e32 v16, v16, v24
	v_fma_f32 v27, v0, v27, v8
	v_mul_f32_e32 v16, v25, v16
	v_cvt_pk_bf16_f32 v27, v27, v27
	v_fma_f32 v16, v1, v16, v9
	ds_write_b16 v28, v27 offset:34816
	v_cvt_pk_bf16_f32 v16, v16, v16
	v_xad_u32 v27, v26, 16, v169
	ds_write_b16 v27, v16 offset:35072
	v_lshlrev_b32_e32 v16, 16, v17
	v_sub_f32_e32 v16, v16, v24
	v_mul_f32_e32 v16, v25, v16
	v_fma_f32 v16, v2, v16, v10
	v_cvt_pk_bf16_f32 v16, v16, v16
	v_xad_u32 v27, v26, 32, v169
	ds_write_b16 v27, v16 offset:35328
	v_and_b32_e32 v16, 0xffff0000, v17
	v_sub_f32_e32 v16, v16, v24
	v_mul_f32_e32 v16, v25, v16
	v_fma_f32 v16, v3, v16, v11
	v_cvt_pk_bf16_f32 v16, v16, v16
	v_xad_u32 v17, v26, 48, v169
	ds_write_b16 v17, v16 offset:35584
	v_lshlrev_b32_e32 v16, 16, v18
	v_sub_f32_e32 v16, v16, v24
	v_mul_f32_e32 v16, v25, v16
	v_fma_f32 v16, v4, v16, v12
	v_cvt_pk_bf16_f32 v16, v16, v16
	v_xad_u32 v17, v26, 64, v169
	ds_write_b16 v17, v16 offset:35840
	v_and_b32_e32 v16, 0xffff0000, v18
	v_sub_f32_e32 v16, v16, v24
	v_mul_f32_e32 v16, v25, v16
	v_fma_f32 v16, v5, v16, v13
	v_cvt_pk_bf16_f32 v16, v16, v16
	v_xad_u32 v17, v26, s20, v169
	ds_write_b16 v17, v16 offset:36096
	v_lshlrev_b32_e32 v16, 16, v19
	v_sub_f32_e32 v16, v16, v24
	v_mul_f32_e32 v16, v25, v16
	v_fma_f32 v16, v6, v16, v14
	v_cvt_pk_bf16_f32 v16, v16, v16
	v_xad_u32 v17, v26, s21, v169
	ds_write_b16 v17, v16 offset:36352
	v_and_b32_e32 v16, 0xffff0000, v19
	v_sub_f32_e32 v16, v16, v24
	v_mul_f32_e32 v16, v25, v16
	v_fma_f32 v16, v7, v16, v15
	v_cvt_pk_bf16_f32 v16, v16, v16
	v_xad_u32 v17, v26, s22, v169
	ds_write_b16 v17, v16 offset:36608
	v_add_u32_e32 v25, 0x19040, v23
	ds_read_b32 v25, v25
	v_add_u32_e32 v23, 0x19240, v23
	ds_read_b32 v23, v23
	v_add_u32_e32 v24, 16, v22
	v_lshrrev_b32_e32 v24, 3, v24
	v_xor_b32_e32 v24, v24, v168
	v_lshlrev_b32_e32 v24, 4, v24
	v_add_u32_e32 v27, v169, v24
	v_add_u32_e32 v22, 32, v22
	v_lshl_add_u64 v[20:21], v[20:21], 0, s[8:9]
	s_waitcnt vmcnt(0)
	v_mov_b32_e32 v16, v244
	v_mov_b32_e32 v17, v245
	v_mov_b32_e32 v18, v246
	v_mov_b32_e32 v19, v247
	v_lshlrev_b32_e32 v26, 16, v16
	s_waitcnt lgkmcnt(1)
	v_sub_f32_e32 v26, v26, v25
	v_and_b32_e32 v16, 0xffff0000, v16
	s_waitcnt lgkmcnt(0)
	v_mul_f32_e32 v26, v23, v26
	v_sub_f32_e32 v16, v16, v25
	v_fma_f32 v26, v0, v26, v8
	v_mul_f32_e32 v16, v23, v16
	v_cvt_pk_bf16_f32 v26, v26, v26
	v_fma_f32 v16, v1, v16, v9
	ds_write_b16 v27, v26 offset:34816
	v_cvt_pk_bf16_f32 v16, v16, v16
	v_xad_u32 v26, v24, 16, v169
	ds_write_b16 v26, v16 offset:35072
	v_lshlrev_b32_e32 v16, 16, v17
	v_sub_f32_e32 v16, v16, v25
	v_mul_f32_e32 v16, v23, v16
	v_fma_f32 v16, v2, v16, v10
	v_cvt_pk_bf16_f32 v16, v16, v16
	v_xad_u32 v26, v24, 32, v169
	ds_write_b16 v26, v16 offset:35328
	v_and_b32_e32 v16, 0xffff0000, v17
	v_sub_f32_e32 v16, v16, v25
	v_mul_f32_e32 v16, v23, v16
	v_fma_f32 v16, v3, v16, v11
	v_cvt_pk_bf16_f32 v16, v16, v16
	v_xad_u32 v17, v24, 48, v169
	ds_write_b16 v17, v16 offset:35584
	v_lshlrev_b32_e32 v16, 16, v18
	v_sub_f32_e32 v16, v16, v25
	v_mul_f32_e32 v16, v23, v16
	v_fma_f32 v16, v4, v16, v12
	v_cvt_pk_bf16_f32 v16, v16, v16
	v_xad_u32 v17, v24, 64, v169
	ds_write_b16 v17, v16 offset:35840
	v_and_b32_e32 v16, 0xffff0000, v18
	v_sub_f32_e32 v16, v16, v25
	v_mul_f32_e32 v16, v23, v16
	v_fma_f32 v16, v5, v16, v13
	v_cvt_pk_bf16_f32 v16, v16, v16
	v_xad_u32 v17, v24, s20, v169
	ds_write_b16 v17, v16 offset:36096
	v_lshlrev_b32_e32 v16, 16, v19
	v_sub_f32_e32 v16, v16, v25
	v_mul_f32_e32 v16, v23, v16
	v_fma_f32 v16, v6, v16, v14
	v_cvt_pk_bf16_f32 v16, v16, v16
	v_xad_u32 v17, v24, s21, v169
	ds_write_b16 v17, v16 offset:36352
	v_and_b32_e32 v16, 0xffff0000, v19
	v_sub_f32_e32 v16, v16, v25
	v_mul_f32_e32 v16, v23, v16
	v_fma_f32 v16, v7, v16, v15
	v_xad_u32 v17, v24, s22, v169
	v_cvt_pk_bf16_f32 v16, v16, v16
	ds_write_b16 v17, v16 offset:36608
	s_waitcnt lgkmcnt(0)
	s_barrier
	ds_read_b128 v[0:3], v178 offset:34816
	ds_read_b128 v[4:7], v179 offset:34816
	ds_read_b128 v[8:11], v180
	ds_read_b128 v[12:15], v180 offset:4352
	ds_read_b128 v[16:19], v180 offset:8704
	ds_read_b128 v[20:23], v180 offset:13056
	ds_read_b128 v[24:27], v180 offset:17408
	ds_read_b128 v[28:31], v180 offset:21760
	ds_read_b128 v[32:35], v180 offset:26112
	ds_read_b128 v[36:39], v180 offset:30464
	s_waitcnt lgkmcnt(7)
	v_mfma_f32_16x16x32_bf16 v[40:43], v[0:3], v[8:11], 0
	s_add_i32 s12, s12, s96
	s_mov_b64 s[74:75], 0
	s_cmpk_gt_i32 s12, 0x7ff
	s_waitcnt lgkmcnt(6)
	v_mfma_f32_16x16x32_bf16 v[44:47], v[0:3], v[12:15], 0
	s_waitcnt lgkmcnt(5)
	v_mfma_f32_16x16x32_bf16 v[48:51], v[0:3], v[16:19], 0
	s_waitcnt lgkmcnt(4)
	v_mfma_f32_16x16x32_bf16 v[52:55], v[0:3], v[20:23], 0
	s_waitcnt lgkmcnt(3)
	v_mfma_f32_16x16x32_bf16 v[56:59], v[0:3], v[24:27], 0
	s_waitcnt lgkmcnt(2)
	v_mfma_f32_16x16x32_bf16 v[60:63], v[0:3], v[28:31], 0
	s_waitcnt lgkmcnt(1)
	v_mfma_f32_16x16x32_bf16 v[64:67], v[0:3], v[32:35], 0
	s_waitcnt lgkmcnt(0)
	v_mfma_f32_16x16x32_bf16 v[0:3], v[0:3], v[36:39], 0
	v_mfma_f32_16x16x32_bf16 v[8:11], v[4:7], v[8:11], 0
	v_mfma_f32_16x16x32_bf16 v[12:15], v[4:7], v[12:15], 0
	v_mfma_f32_16x16x32_bf16 v[16:19], v[4:7], v[16:19], 0
	v_mfma_f32_16x16x32_bf16 v[20:23], v[4:7], v[20:23], 0
	v_mfma_f32_16x16x32_bf16 v[24:27], v[4:7], v[24:27], 0
	v_mfma_f32_16x16x32_bf16 v[28:31], v[4:7], v[28:31], 0
	v_mfma_f32_16x16x32_bf16 v[32:35], v[4:7], v[32:35], 0
	v_mfma_f32_16x16x32_bf16 v[4:7], v[4:7], v[36:39], 0
	ds_read_b128 v[36:39], v181 offset:34816
	ds_read_b128 v[68:71], v182 offset:34816
	ds_read_b128 v[72:75], v180 offset:64
	ds_read_b128 v[76:79], v180 offset:4416
	ds_read_b128 v[80:83], v180 offset:8768
	ds_read_b128 v[132:135], v180 offset:13120
	ds_read_b128 v[136:139], v180 offset:17472
	ds_read_b128 v[142:145], v180 offset:21824
	ds_read_b128 v[146:149], v180 offset:26176
	ds_read_b128 v[150:153], v180 offset:30528
	s_waitcnt lgkmcnt(7)
	v_mfma_f32_16x16x32_bf16 v[40:43], v[36:39], v[72:75], v[40:43]
	s_waitcnt lgkmcnt(6)
	v_mfma_f32_16x16x32_bf16 v[44:47], v[36:39], v[76:79], v[44:47]
	s_waitcnt lgkmcnt(5)
	v_mfma_f32_16x16x32_bf16 v[48:51], v[36:39], v[80:83], v[48:51]
	s_waitcnt lgkmcnt(4)
	v_mfma_f32_16x16x32_bf16 v[52:55], v[36:39], v[132:135], v[52:55]
	s_waitcnt lgkmcnt(3)
	v_mfma_f32_16x16x32_bf16 v[56:59], v[36:39], v[136:139], v[56:59]
	s_waitcnt lgkmcnt(2)
	v_mfma_f32_16x16x32_bf16 v[60:63], v[36:39], v[142:145], v[60:63]
	s_waitcnt lgkmcnt(1)
	v_mfma_f32_16x16x32_bf16 v[64:67], v[36:39], v[146:149], v[64:67]
	s_waitcnt lgkmcnt(0)
	v_mfma_f32_16x16x32_bf16 v[0:3], v[36:39], v[150:153], v[0:3]
	v_mfma_f32_16x16x32_bf16 v[8:11], v[68:71], v[72:75], v[8:11]
	v_mfma_f32_16x16x32_bf16 v[12:15], v[68:71], v[76:79], v[12:15]
	v_mfma_f32_16x16x32_bf16 v[16:19], v[68:71], v[80:83], v[16:19]
	v_mfma_f32_16x16x32_bf16 v[20:23], v[68:71], v[132:135], v[20:23]
	v_mfma_f32_16x16x32_bf16 v[24:27], v[68:71], v[136:139], v[24:27]
	v_mfma_f32_16x16x32_bf16 v[28:31], v[68:71], v[142:145], v[28:31]
	v_mfma_f32_16x16x32_bf16 v[32:35], v[68:71], v[146:149], v[32:35]
	v_mfma_f32_16x16x32_bf16 v[4:7], v[68:71], v[150:153], v[4:7]
	ds_read_b128 v[36:39], v183 offset:34816
	ds_read_b128 v[68:71], v184 offset:34816
	ds_read_b128 v[72:75], v180 offset:128
	ds_read_b128 v[76:79], v180 offset:4480
	ds_read_b128 v[80:83], v180 offset:8832
	ds_read_b128 v[132:135], v180 offset:13184
	ds_read_b128 v[136:139], v180 offset:17536
	ds_read_b128 v[142:145], v180 offset:21888
	ds_read_b128 v[146:149], v180 offset:26240
	ds_read_b128 v[150:153], v180 offset:30592
	s_waitcnt lgkmcnt(7)
	v_mfma_f32_16x16x32_bf16 v[40:43], v[36:39], v[72:75], v[40:43]
	s_waitcnt lgkmcnt(6)
	v_mfma_f32_16x16x32_bf16 v[44:47], v[36:39], v[76:79], v[44:47]
	s_waitcnt lgkmcnt(5)
	v_mfma_f32_16x16x32_bf16 v[48:51], v[36:39], v[80:83], v[48:51]
	s_waitcnt lgkmcnt(4)
	v_mfma_f32_16x16x32_bf16 v[52:55], v[36:39], v[132:135], v[52:55]
	s_waitcnt lgkmcnt(3)
	v_mfma_f32_16x16x32_bf16 v[56:59], v[36:39], v[136:139], v[56:59]
	s_waitcnt lgkmcnt(2)
	v_mfma_f32_16x16x32_bf16 v[154:157], v[36:39], v[142:145], v[60:63]
	s_waitcnt lgkmcnt(1)
	v_mfma_f32_16x16x32_bf16 v[64:67], v[36:39], v[146:149], v[64:67]
	s_waitcnt lgkmcnt(0)
	v_mfma_f32_16x16x32_bf16 v[0:3], v[36:39], v[150:153], v[0:3]
	v_mfma_f32_16x16x32_bf16 v[8:11], v[68:71], v[72:75], v[8:11]
	v_mfma_f32_16x16x32_bf16 v[16:19], v[68:71], v[80:83], v[16:19]
	v_mfma_f32_16x16x32_bf16 v[36:39], v[68:71], v[132:135], v[20:23]
	v_mfma_f32_16x16x32_bf16 v[24:27], v[68:71], v[136:139], v[24:27]
	v_mfma_f32_16x16x32_bf16 v[28:31], v[68:71], v[142:145], v[28:31]
	v_mfma_f32_16x16x32_bf16 v[32:35], v[68:71], v[146:149], v[32:35]
	v_mfma_f32_16x16x32_bf16 v[4:7], v[68:71], v[150:153], v[4:7]
	ds_read_b128 v[20:23], v185 offset:34816
	ds_read_b128 v[132:135], v186 offset:34816
	ds_read_b128 v[72:75], v180 offset:192
	ds_read_b128 v[80:83], v180 offset:4544
	ds_read_b128 v[136:139], v180 offset:8896
	ds_read_b128 v[142:145], v180 offset:13248
	ds_read_b128 v[146:149], v180 offset:17600
	ds_read_b128 v[150:153], v180 offset:21952
	ds_read_b128 v[158:161], v180 offset:26304
	ds_read_b128 v[162:165], v180 offset:30656
	v_mfma_f32_16x16x32_bf16 v[12:15], v[68:71], v[76:79], v[12:15]
	s_waitcnt lgkmcnt(7)
	v_mfma_f32_16x16x32_bf16 v[188:191], v[20:23], v[72:75], v[40:43]
	s_waitcnt lgkmcnt(6)
	v_mfma_f32_16x16x32_bf16 v[192:195], v[20:23], v[80:83], v[44:47]
	s_waitcnt lgkmcnt(5)
	v_mfma_f32_16x16x32_bf16 v[76:79], v[20:23], v[136:139], v[48:51]
	s_waitcnt lgkmcnt(4)
	v_mfma_f32_16x16x32_bf16 v[68:71], v[20:23], v[142:145], v[52:55]
	s_waitcnt lgkmcnt(3)
	v_mfma_f32_16x16x32_bf16 v[60:63], v[20:23], v[146:149], v[56:59]
	s_waitcnt lgkmcnt(2)
	v_mfma_f32_16x16x32_bf16 v[52:55], v[20:23], v[150:153], v[154:157]
	s_waitcnt lgkmcnt(1)
	v_mfma_f32_16x16x32_bf16 v[44:47], v[20:23], v[158:161], v[64:67]
	s_waitcnt lgkmcnt(0)
	v_mfma_f32_16x16x32_bf16 v[20:23], v[20:23], v[162:165], v[0:3]
	v_mfma_f32_16x16x32_bf16 v[56:59], v[132:135], v[146:149], v[24:27]
	v_mfma_f32_16x16x32_bf16 v[24:27], v[132:135], v[162:165], v[4:7]
	v_lshl_add_u64 v[164:165], s[6:7], 0, v[86:87]
	v_lshlrev_b64 v[0:1], 12, v[164:165]
	v_lshl_add_u64 v[0:1], v[88:89], 0, v[0:1]
	v_lshl_add_u64 v[162:163], s[6:7], 0, v[112:113]
	global_load_dwordx4 v[40:43], v[0:1], off
	v_lshlrev_b64 v[0:1], 12, v[162:163]
	v_mfma_f32_16x16x32_bf16 v[64:67], v[132:135], v[142:145], v[36:39]
	v_lshl_add_u64 v[0:1], v[88:89], 0, v[0:1]
	v_mfma_f32_16x16x32_bf16 v[36:39], v[132:135], v[158:161], v[32:35]
	v_lshl_add_u64 v[160:161], s[6:7], 0, v[114:115]
	v_lshl_add_u64 v[158:159], s[6:7], 0, v[116:117]
	s_nop 0
	global_load_dwordx4 v[32:35], v[0:1], off
	v_lshlrev_b64 v[0:1], 12, v[160:161]
	v_lshl_add_u64 v[0:1], v[88:89], 0, v[0:1]
	v_mfma_f32_16x16x32_bf16 v[48:51], v[132:135], v[150:153], v[28:31]
	s_nop 2
	global_load_dwordx4 v[28:31], v[0:1], off
	v_lshlrev_b64 v[0:1], 12, v[158:159]
	v_mfma_f32_16x16x32_bf16 v[154:157], v[132:135], v[72:75], v[8:11]
	v_lshl_add_u64 v[0:1], v[88:89], 0, v[0:1]
	v_mfma_f32_16x16x32_bf16 v[72:75], v[132:135], v[136:139], v[16:19]
	v_lshl_add_u64 v[138:139], s[6:7], 0, v[118:119]
	v_lshl_add_u64 v[136:137], s[6:7], 0, v[120:121]
	s_nop 0
	global_load_dwordx4 v[16:19], v[0:1], off
	v_lshlrev_b64 v[0:1], 12, v[138:139]
	v_lshl_add_u64 v[0:1], v[88:89], 0, v[0:1]
	v_mfma_f32_16x16x32_bf16 v[80:83], v[132:135], v[80:83], v[12:15]
	v_lshl_add_u64 v[134:135], s[6:7], 0, v[122:123]
	v_lshl_add_u64 v[132:133], s[6:7], 0, v[124:125]
	s_nop 0
	global_load_dwordx4 v[12:15], v[0:1], off
	v_lshlrev_b64 v[0:1], 12, v[136:137]
	v_lshl_add_u64 v[0:1], v[88:89], 0, v[0:1]
	global_load_dwordx4 v[8:11], v[0:1], off
	v_lshlrev_b64 v[0:1], 12, v[134:135]
	v_lshl_add_u64 v[0:1], v[88:89], 0, v[0:1]
	global_load_dwordx4 v[4:7], v[0:1], off
	v_lshlrev_b64 v[0:1], 12, v[132:133]
	v_lshl_add_u64 v[0:1], v[88:89], 0, v[0:1]
	global_load_dwordx4 v[0:3], v[0:1], off
	s_barrier
	global_load_dword v142, v[126:127], off
	s_waitcnt vmcnt(0)
	v_pk_add_f32 v[144:145], v[190:191], v[142:143] op_sel_hi:[1,0]
	v_pk_add_f32 v[146:147], v[188:189], v[142:143] op_sel_hi:[1,0]
	s_nop 0
	v_cvt_pk_bf16_f32 v146, v146, v147
	v_cvt_pk_bf16_f32 v147, v144, v145
	v_pk_add_f32 v[144:145], v[156:157], v[142:143] op_sel_hi:[1,0]
	v_pk_add_f32 v[142:143], v[154:155], v[142:143] op_sel_hi:[1,0]
	ds_write_b64 v187, v[146:147] offset:34816
	v_cvt_pk_bf16_f32 v142, v142, v143
	v_cvt_pk_bf16_f32 v143, v144, v145
	ds_write_b64 v187, v[142:143] offset:34848
	global_load_dword v142, v[128:129], off offset:64
	s_waitcnt vmcnt(0)
	v_pk_add_f32 v[146:147], v[192:193], v[142:143] op_sel_hi:[1,0]
	v_pk_add_f32 v[80:81], v[80:81], v[142:143] op_sel_hi:[1,0]
	v_pk_add_f32 v[144:145], v[194:195], v[142:143] op_sel_hi:[1,0]
	v_cvt_pk_bf16_f32 v146, v146, v147
	v_pk_add_f32 v[82:83], v[82:83], v[142:143] op_sel_hi:[1,0]
	v_cvt_pk_bf16_f32 v147, v144, v145
	ds_write_b64 v187, v[146:147] offset:43264
	v_cvt_pk_bf16_f32 v80, v80, v81
	v_cvt_pk_bf16_f32 v81, v82, v83
	ds_write_b64 v187, v[80:81] offset:43296
	global_load_dword v80, v[128:129], off offset:128
	s_waitcnt vmcnt(0)
	v_pk_add_f32 v[76:77], v[76:77], v[80:81] op_sel_hi:[1,0]
	v_pk_add_f32 v[72:73], v[72:73], v[80:81] op_sel_hi:[1,0]
	v_pk_add_f32 v[78:79], v[78:79], v[80:81] op_sel_hi:[1,0]
	v_cvt_pk_bf16_f32 v76, v76, v77
	v_pk_add_f32 v[74:75], v[74:75], v[80:81] op_sel_hi:[1,0]
	v_cvt_pk_bf16_f32 v77, v78, v79
	ds_write_b64 v187, v[76:77] offset:51712
	v_cvt_pk_bf16_f32 v72, v72, v73
	v_cvt_pk_bf16_f32 v73, v74, v75
	ds_write_b64 v187, v[72:73] offset:51744
	global_load_dword v72, v[128:129], off offset:192
	s_waitcnt vmcnt(0)
	v_pk_add_f32 v[68:69], v[68:69], v[72:73] op_sel_hi:[1,0]
	v_pk_add_f32 v[64:65], v[64:65], v[72:73] op_sel_hi:[1,0]
	v_pk_add_f32 v[70:71], v[70:71], v[72:73] op_sel_hi:[1,0]
	v_cvt_pk_bf16_f32 v68, v68, v69
	v_pk_add_f32 v[66:67], v[66:67], v[72:73] op_sel_hi:[1,0]
	v_cvt_pk_bf16_f32 v69, v70, v71
	ds_write_b64 v187, v[68:69] offset:60160
	v_cvt_pk_bf16_f32 v64, v64, v65
	v_cvt_pk_bf16_f32 v65, v66, v67
	ds_write_b64 v187, v[64:65] offset:60192
	global_load_dword v64, v[128:129], off offset:256
	s_waitcnt vmcnt(0)
	v_pk_add_f32 v[60:61], v[60:61], v[64:65] op_sel_hi:[1,0]
	v_pk_add_f32 v[56:57], v[56:57], v[64:65] op_sel_hi:[1,0]
	v_pk_add_f32 v[62:63], v[62:63], v[64:65] op_sel_hi:[1,0]
	v_cvt_pk_bf16_f32 v60, v60, v61
	v_pk_add_f32 v[58:59], v[58:59], v[64:65] op_sel_hi:[1,0]
	v_cvt_pk_bf16_f32 v61, v62, v63
	ds_write_b64 v206, v[60:61] offset:34816
	v_cvt_pk_bf16_f32 v56, v56, v57
	v_cvt_pk_bf16_f32 v57, v58, v59
	ds_write_b64 v206, v[56:57] offset:34848
	global_load_dword v56, v[128:129], off offset:320
	s_waitcnt vmcnt(0)
	v_pk_add_f32 v[52:53], v[52:53], v[56:57] op_sel_hi:[1,0]
	v_pk_add_f32 v[48:49], v[48:49], v[56:57] op_sel_hi:[1,0]
	v_pk_add_f32 v[54:55], v[54:55], v[56:57] op_sel_hi:[1,0]
	v_cvt_pk_bf16_f32 v52, v52, v53
	v_pk_add_f32 v[50:51], v[50:51], v[56:57] op_sel_hi:[1,0]
	v_cvt_pk_bf16_f32 v53, v54, v55
	ds_write_b64 v206, v[52:53] offset:43264
	v_cvt_pk_bf16_f32 v48, v48, v49
	v_cvt_pk_bf16_f32 v49, v50, v51
	ds_write_b64 v206, v[48:49] offset:43296
	global_load_dword v48, v[128:129], off offset:384
	s_waitcnt vmcnt(0)
	v_pk_add_f32 v[44:45], v[44:45], v[48:49] op_sel_hi:[1,0]
	v_pk_add_f32 v[36:37], v[36:37], v[48:49] op_sel_hi:[1,0]
	v_pk_add_f32 v[46:47], v[46:47], v[48:49] op_sel_hi:[1,0]
	v_cvt_pk_bf16_f32 v44, v44, v45
	v_pk_add_f32 v[38:39], v[38:39], v[48:49] op_sel_hi:[1,0]
	v_cvt_pk_bf16_f32 v45, v46, v47
	ds_write_b64 v206, v[44:45] offset:51712
	v_cvt_pk_bf16_f32 v36, v36, v37
	v_cvt_pk_bf16_f32 v37, v38, v39
	ds_write_b64 v206, v[36:37] offset:51744
	global_load_dword v36, v[128:129], off offset:448
	s_waitcnt vmcnt(0)
	v_pk_add_f32 v[22:23], v[22:23], v[36:37] op_sel_hi:[1,0]
	v_pk_add_f32 v[20:21], v[20:21], v[36:37] op_sel_hi:[1,0]
	s_nop 0
	v_cvt_pk_bf16_f32 v20, v20, v21
	v_cvt_pk_bf16_f32 v21, v22, v23
	v_pk_add_f32 v[22:23], v[24:25], v[36:37] op_sel_hi:[1,0]
	ds_write_b64 v206, v[20:21] offset:60160
	v_pk_add_f32 v[20:21], v[26:27], v[36:37] op_sel_hi:[1,0]
	v_cvt_pk_bf16_f32 v22, v22, v23
	v_lshlrev_b32_e32 v24, 16, v40
	v_cvt_pk_bf16_f32 v23, v20, v21
	ds_write_b64 v206, v[22:23] offset:60192
	s_waitcnt lgkmcnt(0)
	s_barrier
	ds_read_b128 v[20:23], v207 offset:34816
	s_waitcnt lgkmcnt(0)
	v_lshlrev_b32_e32 v25, 16, v20
	v_mul_f32_e32 v24, v25, v24
	v_and_b32_e32 v20, 0xffff0000, v20
	v_and_b32_e32 v25, 0xffff0000, v40
	v_mul_f32_e32 v20, v20, v25
	v_cvt_pk_bf16_f32 v20, v24, v20
	v_lshlrev_b32_e32 v24, 16, v41
	v_lshlrev_b32_e32 v25, 16, v21
	v_mul_f32_e32 v24, v25, v24
	v_and_b32_e32 v21, 0xffff0000, v21
	v_and_b32_e32 v25, 0xffff0000, v41
	v_mul_f32_e32 v21, v21, v25
	v_cvt_pk_bf16_f32 v21, v24, v21
	v_lshlrev_b32_e32 v24, 16, v42
	v_lshlrev_b32_e32 v25, 16, v22
	v_mul_f32_e32 v24, v25, v24
	v_and_b32_e32 v22, 0xffff0000, v22
	v_and_b32_e32 v25, 0xffff0000, v42
	v_mul_f32_e32 v22, v22, v25
	v_cvt_pk_bf16_f32 v22, v24, v22
	v_lshlrev_b32_e32 v24, 16, v43
	v_lshlrev_b32_e32 v25, 16, v23
	v_mul_f32_e32 v24, v25, v24
	v_and_b32_e32 v23, 0xffff0000, v23
	v_and_b32_e32 v25, 0xffff0000, v43
	v_mul_f32_e32 v23, v23, v25
	v_cvt_pk_bf16_f32 v23, v24, v23
	v_lshlrev_b64 v[24:25], 11, v[164:165]
	v_lshl_add_u64 v[24:25], v[90:91], 0, v[24:25]
	global_store_dwordx4 v[24:25], v[20:23], off nt
	ds_read_b128 v[20:23], v208 offset:34816
	v_lshlrev_b32_e32 v24, 16, v32
	s_waitcnt lgkmcnt(0)
	v_lshlrev_b32_e32 v25, 16, v20
	v_mul_f32_e32 v24, v25, v24
	v_and_b32_e32 v20, 0xffff0000, v20
	v_and_b32_e32 v25, 0xffff0000, v32
	v_mul_f32_e32 v20, v20, v25
	v_cvt_pk_bf16_f32 v20, v24, v20
	v_lshlrev_b32_e32 v24, 16, v33
	v_lshlrev_b32_e32 v25, 16, v21
	v_mul_f32_e32 v24, v25, v24
	v_and_b32_e32 v21, 0xffff0000, v21
	v_and_b32_e32 v25, 0xffff0000, v33
	v_mul_f32_e32 v21, v21, v25
	v_cvt_pk_bf16_f32 v21, v24, v21
	v_lshlrev_b32_e32 v24, 16, v34
	v_lshlrev_b32_e32 v25, 16, v22
	v_mul_f32_e32 v24, v25, v24
	v_and_b32_e32 v22, 0xffff0000, v22
	v_and_b32_e32 v25, 0xffff0000, v34
	v_mul_f32_e32 v22, v22, v25
	v_cvt_pk_bf16_f32 v22, v24, v22
	v_lshlrev_b32_e32 v24, 16, v35
	v_lshlrev_b32_e32 v25, 16, v23
	v_mul_f32_e32 v24, v25, v24
	v_and_b32_e32 v23, 0xffff0000, v23
	v_and_b32_e32 v25, 0xffff0000, v35
	v_mul_f32_e32 v23, v23, v25
	v_cvt_pk_bf16_f32 v23, v24, v23
	v_lshlrev_b64 v[24:25], 11, v[162:163]
	v_lshl_add_u64 v[24:25], v[90:91], 0, v[24:25]
	global_store_dwordx4 v[24:25], v[20:23], off nt
	ds_read_b128 v[20:23], v209 offset:34816
	v_lshlrev_b32_e32 v24, 16, v28
	s_waitcnt lgkmcnt(0)
	v_lshlrev_b32_e32 v25, 16, v20
	v_mul_f32_e32 v24, v25, v24
	v_and_b32_e32 v20, 0xffff0000, v20
	v_and_b32_e32 v25, 0xffff0000, v28
	v_mul_f32_e32 v20, v20, v25
	v_cvt_pk_bf16_f32 v20, v24, v20
	v_lshlrev_b32_e32 v24, 16, v29
	v_lshlrev_b32_e32 v25, 16, v21
	v_mul_f32_e32 v24, v25, v24
	v_and_b32_e32 v21, 0xffff0000, v21
	v_and_b32_e32 v25, 0xffff0000, v29
	v_mul_f32_e32 v21, v21, v25
	v_cvt_pk_bf16_f32 v21, v24, v21
	v_lshlrev_b32_e32 v24, 16, v30
	v_lshlrev_b32_e32 v25, 16, v22
	v_mul_f32_e32 v24, v25, v24
	v_and_b32_e32 v22, 0xffff0000, v22
	v_and_b32_e32 v25, 0xffff0000, v30
	v_mul_f32_e32 v22, v22, v25
	v_cvt_pk_bf16_f32 v22, v24, v22
	v_lshlrev_b32_e32 v24, 16, v31
	v_lshlrev_b32_e32 v25, 16, v23
	v_mul_f32_e32 v24, v25, v24
	v_and_b32_e32 v23, 0xffff0000, v23
	v_and_b32_e32 v25, 0xffff0000, v31
	v_mul_f32_e32 v23, v23, v25
	v_cvt_pk_bf16_f32 v23, v24, v23
	v_lshlrev_b64 v[24:25], 11, v[160:161]
	v_lshl_add_u64 v[24:25], v[90:91], 0, v[24:25]
	global_store_dwordx4 v[24:25], v[20:23], off nt
	ds_read_b128 v[20:23], v210 offset:34816
	v_lshlrev_b32_e32 v24, 16, v16
	v_and_b32_e32 v16, 0xffff0000, v16
	s_waitcnt lgkmcnt(0)
	v_lshlrev_b32_e32 v25, 16, v20
	v_and_b32_e32 v20, 0xffff0000, v20
	v_mul_f32_e32 v24, v25, v24
	v_mul_f32_e32 v16, v20, v16
	v_cvt_pk_bf16_f32 v16, v24, v16
	v_lshlrev_b32_e32 v20, 16, v17
	v_lshlrev_b32_e32 v24, 16, v21
	v_and_b32_e32 v21, 0xffff0000, v21
	v_and_b32_e32 v17, 0xffff0000, v17
	v_mul_f32_e32 v20, v24, v20
	v_mul_f32_e32 v17, v21, v17
	v_cvt_pk_bf16_f32 v17, v20, v17
	v_lshlrev_b32_e32 v20, 16, v18
	v_lshlrev_b32_e32 v21, 16, v22
	v_mul_f32_e32 v20, v21, v20
	v_and_b32_e32 v21, 0xffff0000, v22
	v_and_b32_e32 v18, 0xffff0000, v18
	v_mul_f32_e32 v18, v21, v18
	v_cvt_pk_bf16_f32 v18, v20, v18
	v_lshlrev_b32_e32 v20, 16, v19
	v_lshlrev_b32_e32 v21, 16, v23
	v_mul_f32_e32 v20, v21, v20
	v_and_b32_e32 v21, 0xffff0000, v23
	v_and_b32_e32 v19, 0xffff0000, v19
	v_mul_f32_e32 v19, v21, v19
	v_cvt_pk_bf16_f32 v19, v20, v19
	v_lshlrev_b64 v[20:21], 11, v[158:159]
	v_lshl_add_u64 v[20:21], v[90:91], 0, v[20:21]
	global_store_dwordx4 v[20:21], v[16:19], off nt
	ds_read_b128 v[16:19], v211 offset:34816
	v_lshlrev_b32_e32 v20, 16, v12
	v_and_b32_e32 v12, 0xffff0000, v12
	s_waitcnt lgkmcnt(0)
	v_lshlrev_b32_e32 v21, 16, v16
	v_and_b32_e32 v16, 0xffff0000, v16
	v_mul_f32_e32 v20, v21, v20
	v_mul_f32_e32 v12, v16, v12
	v_cvt_pk_bf16_f32 v12, v20, v12
	v_lshlrev_b32_e32 v16, 16, v13
	v_lshlrev_b32_e32 v20, 16, v17
	v_and_b32_e32 v17, 0xffff0000, v17
	v_and_b32_e32 v13, 0xffff0000, v13
	v_mul_f32_e32 v16, v20, v16
	v_mul_f32_e32 v13, v17, v13
	v_cvt_pk_bf16_f32 v13, v16, v13
	v_lshlrev_b32_e32 v16, 16, v14
	v_lshlrev_b32_e32 v17, 16, v18
	v_mul_f32_e32 v16, v17, v16
	v_and_b32_e32 v17, 0xffff0000, v18
	v_and_b32_e32 v14, 0xffff0000, v14
	v_mul_f32_e32 v14, v17, v14
	v_cvt_pk_bf16_f32 v14, v16, v14
	v_lshlrev_b32_e32 v16, 16, v15
	v_lshlrev_b32_e32 v17, 16, v19
	v_mul_f32_e32 v16, v17, v16
	v_and_b32_e32 v17, 0xffff0000, v19
	v_and_b32_e32 v15, 0xffff0000, v15
	v_mul_f32_e32 v15, v17, v15
	v_cvt_pk_bf16_f32 v15, v16, v15
	v_lshlrev_b64 v[16:17], 11, v[138:139]
	v_lshl_add_u64 v[16:17], v[90:91], 0, v[16:17]
	global_store_dwordx4 v[16:17], v[12:15], off nt
	ds_read_b128 v[12:15], v212 offset:34816
	v_lshlrev_b32_e32 v16, 16, v8
	v_and_b32_e32 v8, 0xffff0000, v8
	s_waitcnt lgkmcnt(0)
	v_lshlrev_b32_e32 v17, 16, v12
	v_and_b32_e32 v12, 0xffff0000, v12
	v_mul_f32_e32 v16, v17, v16
	v_mul_f32_e32 v8, v12, v8
	v_cvt_pk_bf16_f32 v8, v16, v8
	v_lshlrev_b32_e32 v12, 16, v9
	v_lshlrev_b32_e32 v16, 16, v13
	v_and_b32_e32 v13, 0xffff0000, v13
	v_and_b32_e32 v9, 0xffff0000, v9
	v_mul_f32_e32 v12, v16, v12
	v_mul_f32_e32 v9, v13, v9
	v_cvt_pk_bf16_f32 v9, v12, v9
	v_lshlrev_b32_e32 v12, 16, v10
	v_lshlrev_b32_e32 v13, 16, v14
	v_mul_f32_e32 v12, v13, v12
	v_and_b32_e32 v13, 0xffff0000, v14
	v_and_b32_e32 v10, 0xffff0000, v10
	v_mul_f32_e32 v10, v13, v10
	v_cvt_pk_bf16_f32 v10, v12, v10
	v_lshlrev_b32_e32 v12, 16, v11
	v_lshlrev_b32_e32 v13, 16, v15
	v_mul_f32_e32 v12, v13, v12
	v_and_b32_e32 v13, 0xffff0000, v15
	v_and_b32_e32 v11, 0xffff0000, v11
	v_mul_f32_e32 v11, v13, v11
	v_cvt_pk_bf16_f32 v11, v12, v11
	v_lshlrev_b64 v[12:13], 11, v[136:137]
	v_lshl_add_u64 v[12:13], v[90:91], 0, v[12:13]
	global_store_dwordx4 v[12:13], v[8:11], off nt
	ds_read_b128 v[8:11], v213 offset:34816
	v_lshlrev_b32_e32 v12, 16, v4
	v_and_b32_e32 v4, 0xffff0000, v4
	s_waitcnt lgkmcnt(0)
	v_lshlrev_b32_e32 v13, 16, v8
	v_and_b32_e32 v8, 0xffff0000, v8
	v_mul_f32_e32 v12, v13, v12
	v_mul_f32_e32 v4, v8, v4
	v_cvt_pk_bf16_f32 v4, v12, v4
	v_lshlrev_b32_e32 v8, 16, v5
	v_lshlrev_b32_e32 v12, 16, v9
	v_and_b32_e32 v9, 0xffff0000, v9
	v_and_b32_e32 v5, 0xffff0000, v5
	v_mul_f32_e32 v8, v12, v8
	v_mul_f32_e32 v5, v9, v5
	v_cvt_pk_bf16_f32 v5, v8, v5
	v_lshlrev_b32_e32 v8, 16, v6
	v_lshlrev_b32_e32 v9, 16, v10
	v_mul_f32_e32 v8, v9, v8
	v_and_b32_e32 v9, 0xffff0000, v10
	v_and_b32_e32 v6, 0xffff0000, v6
	v_mul_f32_e32 v6, v9, v6
	v_cvt_pk_bf16_f32 v6, v8, v6
	v_lshlrev_b32_e32 v8, 16, v7
	v_lshlrev_b32_e32 v9, 16, v11
	v_mul_f32_e32 v8, v9, v8
	v_and_b32_e32 v9, 0xffff0000, v11
	v_and_b32_e32 v7, 0xffff0000, v7
	v_mul_f32_e32 v7, v9, v7
	v_cvt_pk_bf16_f32 v7, v8, v7
	v_lshlrev_b64 v[8:9], 11, v[134:135]
	v_lshl_add_u64 v[8:9], v[90:91], 0, v[8:9]
	global_store_dwordx4 v[8:9], v[4:7], off nt
	ds_read_b128 v[4:7], v214 offset:34816
	v_lshlrev_b32_e32 v8, 16, v0
	v_and_b32_e32 v0, 0xffff0000, v0
	s_waitcnt lgkmcnt(0)
	v_lshlrev_b32_e32 v9, 16, v4
	v_and_b32_e32 v4, 0xffff0000, v4
	v_mul_f32_e32 v8, v9, v8
	v_mul_f32_e32 v0, v4, v0
	v_cvt_pk_bf16_f32 v0, v8, v0
	v_lshlrev_b32_e32 v4, 16, v1
	v_lshlrev_b32_e32 v8, 16, v5
	v_and_b32_e32 v5, 0xffff0000, v5
	v_and_b32_e32 v1, 0xffff0000, v1
	v_mul_f32_e32 v4, v8, v4
	v_mul_f32_e32 v1, v5, v1
	v_cvt_pk_bf16_f32 v1, v4, v1
	v_lshlrev_b32_e32 v4, 16, v2
	v_lshlrev_b32_e32 v5, 16, v6
	v_mul_f32_e32 v4, v5, v4
	v_and_b32_e32 v5, 0xffff0000, v6
	v_and_b32_e32 v2, 0xffff0000, v2
	v_mul_f32_e32 v2, v5, v2
	v_cvt_pk_bf16_f32 v2, v4, v2
	v_lshlrev_b32_e32 v4, 16, v3
	v_lshlrev_b32_e32 v5, 16, v7
	v_mul_f32_e32 v4, v5, v4
	v_and_b32_e32 v5, 0xffff0000, v7
	v_and_b32_e32 v3, 0xffff0000, v3
	v_mul_f32_e32 v3, v5, v3
	v_cvt_pk_bf16_f32 v3, v4, v3
	v_lshlrev_b64 v[4:5], 11, v[132:133]
	v_lshl_add_u64 v[4:5], v[90:91], 0, v[4:5]
	global_store_dwordx4 v[4:5], v[0:3], off nt
	s_cbranch_scc0 .LBB0_482
	s_mov_b32 s50, s24
	s_mov_b32 s52, s28

	.amdhsa_kernel _Z14fwd_megakernel6Params
		.amdhsa_group_segment_fixed_size 0
		.amdhsa_private_segment_fixed_size 0
		.amdhsa_kernarg_size 440
		.amdhsa_user_sgpr_count 2
		.amdhsa_user_sgpr_dispatch_ptr 0
		.amdhsa_user_sgpr_queue_ptr 0
		.amdhsa_user_sgpr_kernarg_segment_ptr 1
		.amdhsa_user_sgpr_dispatch_id 0
		.amdhsa_user_sgpr_kernarg_preload_length 0
		.amdhsa_user_sgpr_kernarg_preload_offset 0
		.amdhsa_user_sgpr_private_segment_size 0
		.amdhsa_uses_dynamic_stack 0
		.amdhsa_enable_private_segment 0
		.amdhsa_system_sgpr_workgroup_id_x 1
		.amdhsa_system_sgpr_workgroup_id_y 0
		.amdhsa_system_sgpr_workgroup_id_z 0
		.amdhsa_system_sgpr_workgroup_info 0
		.amdhsa_system_vgpr_workitem_id 2
		.amdhsa_next_free_vgpr 256
		.amdhsa_next_free_sgpr 102
		.amdhsa_accum_offset 256
		.amdhsa_reserve_vcc 1
		.amdhsa_float_round_mode_32 0
		.amdhsa_float_round_mode_16_64 0
		.amdhsa_float_denorm_mode_32 3
		.amdhsa_float_denorm_mode_16_64 3
		.amdhsa_dx10_clamp 1
		.amdhsa_ieee_mode 1
		.amdhsa_fp16_overflow 0
		.amdhsa_tg_split 0
		.amdhsa_exception_fp_ieee_invalid_op 0
		.amdhsa_exception_fp_denorm_src 0
		.amdhsa_exception_fp_ieee_div_zero 0
		.amdhsa_exception_fp_ieee_overflow 0
		.amdhsa_exception_fp_ieee_underflow 0
		.amdhsa_exception_fp_ieee_inexact 0
		.amdhsa_exception_int_div_zero 0
	.end_amdhsa_kernel

amdhsa.kernels:
  - .agpr_count:     0
    .args:
      - .offset:         0
        .size:           184
        .value_kind:     by_value
      - .offset:         184
        .size:           4
        .value_kind:     hidden_block_count_x
      - .offset:         188
        .size:           4
        .value_kind:     hidden_block_count_y
      - .offset:         192
        .size:           4
        .value_kind:     hidden_block_count_z
      - .offset:         196
        .size:           2
        .value_kind:     hidden_group_size_x
      - .offset:         198
        .size:           2
        .value_kind:     hidden_group_size_y
      - .offset:         200
        .size:           2
        .value_kind:     hidden_group_size_z
      - .offset:         202
        .size:           2
        .value_kind:     hidden_remainder_x
      - .offset:         204
        .size:           2
        .value_kind:     hidden_remainder_y
      - .offset:         206
        .size:           2
        .value_kind:     hidden_remainder_z
      - .offset:         224
        .size:           8
        .value_kind:     hidden_global_offset_x
      - .offset:         232
        .size:           8
        .value_kind:     hidden_global_offset_y
      - .offset:         240
        .size:           8
        .value_kind:     hidden_global_offset_z
      - .offset:         248
        .size:           2
        .value_kind:     hidden_grid_dims
      - .offset:         272
        .size:           8
        .value_kind:     hidden_multigrid_sync_arg
      - .offset:         304
        .size:           4
        .value_kind:     hidden_dynamic_lds_size
    .group_segment_fixed_size: 0
    .kernarg_segment_align: 8
    .kernarg_segment_size: 440
    .language:       OpenCL C
    .language_version:
      - 2
      - 0
    .max_flat_workgroup_size: 512
    .name:           _Z14fwd_megakernel6Params
    .private_segment_fixed_size: 0
    .sgpr_count:     108
    .sgpr_spill_count: 183
    .symbol:         _Z14fwd_megakernel6Params.kd
    .uniform_work_group_size: 1
    .uses_dynamic_stack: false
    .vgpr_count:     256
    .vgpr_spill_count: 0
    .wavefront_size: 64
